# v16 + ppass(retention): transposed MFMA output, 8 two-byte stores per lane replaced by 2 eight-byte stores
# baseline (speedup 1.0000x reference)
; DI bf16_t tobf(float f) { return (bf16_t)(pk(f, 0.f) & 0xffffu); }
; template <int DK, bool GLA>
; DI void ppass_phase(const bf16_t* Qf, const bf16_t* Kf, const bf16_t* Qb, const bf16_t* Kb, int ld, const float* decay, bf16_t* P) {
;     ...
;   for (int item = blockIdx.x; item < 2048; item += gridDim.x) {
;     const int n = item & 127, h = (item >> 7) & 3, b = item >> 9;
;     const size_t tok0 = (size_t)b * L_ + n * 64;
;     f32x4 xf[2] = {}, xb[2] = {};
;     const bf16_t* qa = Qf + (tok0 + 16 * rt + fr) * ld + h * DK + 8 * fq;
;     const bf16_t* ka0 = Kf + (tok0 + 16 * ct0 + fr) * ld + h * DK + 8 * fq;
;     const bf16_t* ka1 = ka0 + (size_t)16 * ld;
; #pragma unroll
;     for (int kk = 0; kk < DK / 32; ++kk) {
;       const bf16x8 a = gld<bf16x8>(qa + 32 * kk), b0 = gld<bf16x8>(ka0 + 32 * kk), b1 = gld<bf16x8>(ka1 + 32 * kk);
;       xf[0] = __builtin_amdgcn_mfma_f32_16x16x32_bf16(a, b0, xf[0], 0, 0, 0);
;       xf[1] = __builtin_amdgcn_mfma_f32_16x16x32_bf16(a, b1, xf[1], 0, 0, 0);
;     }
;     if (GLA) {
;       const bf16_t* qb = Qb + (tok0 + 16 * rt + fr) * ld + h * DK + 8 * fq;
;       const bf16_t* kb0 = Kb + (tok0 + 16 * ct0 + fr) * ld + h * DK + 8 * fq;
;       const bf16_t* kb1 = kb0 + (size_t)16 * ld;
; #pragma unroll
;       for (int kk = 0; kk < DK / 32; ++kk) {
;         const bf16x8 a = gld<bf16x8>(qb + 32 * kk), b0 = gld<bf16x8>(kb0 + 32 * kk), b1 = gld<bf16x8>(kb1 + 32 * kk);
;         xb[0] = __builtin_amdgcn_mfma_f32_16x16x32_bf16(a, b0, xb[0], 0, 0, 0);
;         xb[1] = __builtin_amdgcn_mfma_f32_16x16x32_bf16(a, b1, xb[1], 0, 0, 0);
;       }
;     }
;     bf16_t* Po = P + (size_t)item * 4096;
;     Po = P + ((size_t)((b * 128 + n) * 4 + h)) * 4096;
; #pragma unroll
;     for (int c = 0; c < 2; ++c)
; #pragma unroll
;       for (int j = 0; j < 4; ++j) {
;         const int i = 16 * rt + 4 * fq + j, s = 16 * (ct0 + c) + fr;
;         float v;
;         if (GLA) v = (s <= i) ? xf[c][j] : xb[c][j];
;         else v = xf[c][j];
;         gst<bf16_t>(Po + i * 64 + s, tobf(v));
;       }
;   }
.LBB0_978:
	s_mov_b64 s[4:5], 0
	v_writelane_b32 v255, s4, 33
	s_and_b64 vcc, exec, s[42:43]
	s_nop 0
	v_writelane_b32 v255, s5, 34
	s_cbranch_vccz .LBB0_987
	s_cmp_gt_i32 s91, 0
	s_mov_b64 s[22:23], -1
	s_cbranch_scc0 .LBB0_984
	v_readlane_b32 s4, v254, 58
	v_readlane_b32 s5, v254, 59
	v_mov_b32_e32 v2, v159
	s_andn2_b64 vcc, exec, s[4:5]
	s_cbranch_vccnz .LBB0_983
	v_ashrrev_i32_e32 v0, 3, v2
	v_and_b32_e32 v3, 15, v2
	v_bfe_u32 v4, v2, 4, 2
	v_and_b32_e32 v5, -16, v0
	v_lshrrev_b32_e32 v2, 1, v2
	v_or_b32_e32 v0, v5, v3
	v_and_or_b32 v2, v2, 32, v3
	v_lshlrev_b32_e32 v3, 6, v5
	v_readlane_b32 s4, v255, 41
	v_lshlrev_b32_e32 v6, 3, v4
	v_lshl_or_b32 v4, v4, 8, v3
	v_lshlrev_b32_e32 v148, 1, v2
	v_readlane_b32 s5, v255, 42
	s_add_u32 s22, s20, 0x2000800
	s_waitcnt lgkmcnt(0)
	v_ashrrev_i32_e32 v1, 31, v5
	v_ashrrev_i32_e32 v5, 31, v4
	v_lshl_add_u64 v[8:9], s[4:5], 0, v[148:149]
	s_addc_u32 s23, s21, 0
	v_lshl_add_u64 v[4:5], v[4:5], 1, v[8:9]
	v_lshrrev_b32_e32 v50, 7, v159
	v_lshlrev_b32_e32 v50, 11, v50
	v_and_b32_e32 v51, 15, v159
	v_lshl_or_b32 v50, v51, 7, v50
	v_and_b32_e32 v51, 64, v159
	v_or_b32_e32 v50, v50, v51
	v_bfe_u32 v51, v159, 4, 2
	v_lshl_or_b32 v50, v51, 3, v50
	v_mov_b32_e32 v51, 0
	v_lshl_add_u64 v[48:49], s[4:5], 0, v[50:51]
	v_lshlrev_b32_e32 v148, 1, v6
	s_mov_b32 s4, s2
.LBB0_982:
	s_ashr_i32 s26, s4, 9
	s_and_b32 s5, s4, 0x7f
	s_ashr_i32 s27, s26, 31
	s_lshl_b32 s39, s5, 6
	s_lshl_b64 s[26:27], s[26:27], 13
	s_or_b32 s26, s26, s39
	v_mov_b32_e32 v7, s27
	v_or_b32_e32 v6, s26, v2
	s_bfe_u32 s38, s4, 0x20007
	v_lshl_add_u64 v[8:9], v[0:1], 0, s[26:27]
	v_lshlrev_b64 v[6:7], 12, v[6:7]
	s_lshl_b32 s24, s38, 9
	v_lshlrev_b64 v[8:9], 12, v[8:9]
	v_lshl_add_u64 v[6:7], s[22:23], 0, v[6:7]
	v_lshl_add_u64 v[8:9], s[34:35], 0, v[8:9]
	v_lshl_add_u64 v[6:7], v[6:7], 0, s[24:25]
	v_lshl_add_u64 v[8:9], v[8:9], 0, s[24:25]
	v_lshl_add_u64 v[44:45], v[6:7], 0, v[148:149]
	s_mov_b32 s24, 0x10000
	v_lshl_add_u64 v[42:43], v[8:9], 0, v[148:149]
	v_add_co_u32_e32 v46, vcc, s24, v44
	global_load_dwordx4 v[6:9], v[42:43], off
	global_load_dwordx4 v[10:13], v[44:45], off
	v_addc_co_u32_e32 v47, vcc, 0, v45, vcc
	global_load_dwordx4 v[14:17], v[42:43], off offset:64
	global_load_dwordx4 v[18:21], v[44:45], off offset:64
	global_load_dwordx4 v[22:25], v[42:43], off offset:128
	global_load_dwordx4 v[26:29], v[46:47], off
	global_load_dwordx4 v[30:33], v[46:47], off offset:64
	s_and_b32 s24, s4, 0xfffffe00
	s_lshl_b32 s5, s5, 2
	s_or_b32 s5, s5, s24
	s_or_b32 s26, s5, s38
	s_ashr_i32 s27, s26, 31
	s_add_i32 s4, s4, s78
	s_lshl_b64 s[26:27], s[26:27], 13
	s_cmpk_gt_i32 s4, 0x7ff
	s_waitcnt vmcnt(0)
	v_mfma_f32_16x16x32_bf16 v[10:13], v[10:13], v[6:9], 0
	v_mfma_f32_16x16x32_bf16 v[6:9], v[26:29], v[6:9], 0
	global_load_dwordx4 v[26:29], v[44:45], off offset:128
	v_mfma_f32_16x16x32_bf16 v[10:13], v[18:21], v[14:17], v[10:13]
	global_load_dwordx4 v[18:21], v[42:43], off offset:192
	global_load_dwordx4 v[34:37], v[44:45], off offset:192
	global_load_dwordx4 v[38:41], v[42:43], off offset:256
	v_mfma_f32_16x16x32_bf16 v[6:9], v[30:33], v[14:17], v[6:9]
	global_load_dwordx4 v[14:17], v[46:47], off offset:128
	s_waitcnt vmcnt(4)
	v_mfma_f32_16x16x32_bf16 v[10:13], v[26:29], v[22:25], v[10:13]
	global_load_dwordx4 v[26:29], v[46:47], off offset:192
	s_waitcnt vmcnt(1)
	v_mfma_f32_16x16x32_bf16 v[6:9], v[14:17], v[22:25], v[6:9]
	global_load_dwordx4 v[14:17], v[44:45], off offset:256
	v_mfma_f32_16x16x32_bf16 v[10:13], v[34:37], v[18:21], v[10:13]
	global_load_dwordx4 v[22:25], v[42:43], off offset:320
	global_load_dwordx4 v[30:33], v[44:45], off offset:320
	global_load_dwordx4 v[34:37], v[42:43], off offset:384
	s_waitcnt vmcnt(4)
	v_mfma_f32_16x16x32_bf16 v[6:9], v[26:29], v[18:21], v[6:9]
	global_load_dwordx4 v[18:21], v[46:47], off offset:256
	s_waitcnt vmcnt(4)
	v_mfma_f32_16x16x32_bf16 v[10:13], v[14:17], v[38:41], v[10:13]
	global_load_dwordx4 v[14:17], v[46:47], off offset:320
	s_waitcnt vmcnt(3)
	v_mfma_f32_16x16x32_bf16 v[10:13], v[30:33], v[22:25], v[10:13]
	s_waitcnt vmcnt(1)
	v_mfma_f32_16x16x32_bf16 v[6:9], v[18:21], v[38:41], v[6:9]
	global_load_dwordx4 v[18:21], v[44:45], off offset:384
	global_load_dwordx4 v[26:29], v[42:43], off offset:448
	global_load_dwordx4 v[38:41], v[44:45], off offset:448
	global_load_dwordx4 v[30:33], v[46:47], off offset:384
	s_waitcnt vmcnt(4)
	v_mfma_f32_16x16x32_bf16 v[6:9], v[14:17], v[22:25], v[6:9]
	global_load_dwordx4 v[14:17], v[46:47], off offset:448
	s_waitcnt vmcnt(4)
	v_mfma_f32_16x16x32_bf16 v[10:13], v[18:21], v[34:37], v[10:13]
	v_lshl_add_u64 v[18:19], v[48:49], 0, s[26:27]
	s_waitcnt vmcnt(1)
	v_mfma_f32_16x16x32_bf16 v[6:9], v[30:33], v[34:37], v[6:9]
	v_mfma_f32_16x16x32_bf16 v[10:13], v[38:41], v[26:29], v[10:13]
	s_waitcnt vmcnt(0)
	v_mfma_f32_16x16x32_bf16 v[6:9], v[14:17], v[26:29], v[6:9]
	s_nop 7
	v_cvt_pk_bf16_f32 v10, v10, v11
	v_cvt_pk_bf16_f32 v11, v12, v13
	v_cvt_pk_bf16_f32 v6, v6, v7
	v_cvt_pk_bf16_f32 v7, v8, v9
	global_store_dwordx2 v[18:19], v[10:11], off
	global_store_dwordx2 v[18:19], v[6:7], off offset:32
	s_cbranch_scc0 .LBB0_982
